# P1 V^T epilogue: in-quad 4x4 transposition (DPP+v_perm), 32 eight-byte stores per lane instead of 128 two-byte stores
# baseline (speedup 1.0000x reference)
.LBB0_139:
	s_ashr_i32 s1, s0, 31
	s_lshr_b32 s1, s1, 30
	s_add_i32 s1, s0, s1
	s_lshl_b32 s1, s1, 2
	s_lshl_b32 s2, s0, 2
	s_and_b32 s1, s1, -16
	s_sub_i32 s1, s2, s1
	s_or_b32 s69, s1, s90
	s_lshl_b32 s1, s76, 8
	s_add_i32 s1, s1, s91
	v_or_b32_e32 v196, s1, v169
	s_cmp_lt_i32 s0, 8
	s_mov_b64 s[2:3], -1
	s_cbranch_scc1 .LBB0_141
	s_ashr_i32 s1, s1, 9
	s_and_b32 s1, s1, -16
	s_add_i32 s2, s1, s69
	s_ashr_i32 s3, s2, 31
	s_lshl_b64 s[2:3], s[2:3], 20
	v_and_or_b32 v0, v196, s41, v208
	v_lshl_add_u64 v[2:3], v[182:183], 0, s[2:3]
	v_lshlrev_b32_e32 v0, 1, v0
	v_lshl_add_u64 v[2:3], v[2:3], 0, v[0:1]
	v_and_b32_e32 v0, 3, v215
	v_mul_u32_u24_e32 v0, 0x3ffe, v0
	v_add_co_u32_e32 v2, vcc, v2, v0
	s_nop 1
	v_addc_co_u32_e32 v3, vcc, 0, v3, vcc
	v_add_co_u32_e32 v148, vcc, 0x10000, v2
	s_nop 1
	v_addc_co_u32_e32 v149, vcc, 0, v3, vcc
	v_add_co_u32_e32 v150, vcc, 0x80000, v2
	s_nop 1
	v_addc_co_u32_e32 v151, vcc, 0, v3, vcc
	v_add_co_u32_e32 v152, vcc, 0x90000, v2
	s_nop 1
	v_addc_co_u32_e32 v153, vcc, 0, v3, vcc
	v_and_b32_e32 v0, 1, v215
	v_mov_b32_e32 v154, 0x5040100
	v_mov_b32_e32 v155, 0x3020706
	v_cmp_eq_u32_e32 vcc, 1, v0
	v_and_b32_e32 v0, 2, v215
	s_nop 1
	v_cndmask_b32_e32 v154, v154, v155, vcc
	v_cmp_ne_u32_e32 vcc, 0, v0
	s_nop 1
	v_cvt_pk_bf16_f32 v132, v128, v129
	v_cvt_pk_bf16_f32 v134, v130, v131
	v_cvt_pk_bf16_f32 v136, v124, v125
	v_cvt_pk_bf16_f32 v138, v126, v127
	v_cvt_pk_bf16_f32 v140, v104, v105
	v_cvt_pk_bf16_f32 v142, v106, v107
	v_cvt_pk_bf16_f32 v144, v84, v85
	v_cvt_pk_bf16_f32 v146, v86, v87
	v_mov_b32_dpp v133, v132 quad_perm:[1,0,3,2] row_mask:0xf bank_mask:0xf
	v_mov_b32_dpp v135, v134 quad_perm:[1,0,3,2] row_mask:0xf bank_mask:0xf
	v_mov_b32_dpp v137, v136 quad_perm:[1,0,3,2] row_mask:0xf bank_mask:0xf
	v_mov_b32_dpp v139, v138 quad_perm:[1,0,3,2] row_mask:0xf bank_mask:0xf
	v_mov_b32_dpp v141, v140 quad_perm:[1,0,3,2] row_mask:0xf bank_mask:0xf
	v_mov_b32_dpp v143, v142 quad_perm:[1,0,3,2] row_mask:0xf bank_mask:0xf
	v_mov_b32_dpp v145, v144 quad_perm:[1,0,3,2] row_mask:0xf bank_mask:0xf
	v_mov_b32_dpp v147, v146 quad_perm:[1,0,3,2] row_mask:0xf bank_mask:0xf
	v_perm_b32 v132, v133, v132, v154
	v_perm_b32 v134, v135, v134, v154
	v_perm_b32 v136, v137, v136, v154
	v_perm_b32 v138, v139, v138, v154
	v_perm_b32 v140, v141, v140, v154
	v_perm_b32 v142, v143, v142, v154
	v_perm_b32 v144, v145, v144, v154
	v_perm_b32 v146, v147, v146, v154
	v_mov_b32_dpp v133, v132 quad_perm:[2,3,0,1] row_mask:0xf bank_mask:0xf
	v_mov_b32_dpp v135, v134 quad_perm:[2,3,0,1] row_mask:0xf bank_mask:0xf
	v_mov_b32_dpp v137, v136 quad_perm:[2,3,0,1] row_mask:0xf bank_mask:0xf
	v_mov_b32_dpp v139, v138 quad_perm:[2,3,0,1] row_mask:0xf bank_mask:0xf
	v_mov_b32_dpp v141, v140 quad_perm:[2,3,0,1] row_mask:0xf bank_mask:0xf
	v_mov_b32_dpp v143, v142 quad_perm:[2,3,0,1] row_mask:0xf bank_mask:0xf
	v_mov_b32_dpp v145, v144 quad_perm:[2,3,0,1] row_mask:0xf bank_mask:0xf
	v_mov_b32_dpp v147, v146 quad_perm:[2,3,0,1] row_mask:0xf bank_mask:0xf
	v_cndmask_b32_e32 v132, v132, v135, vcc
	v_cndmask_b32_e32 v133, v133, v134, vcc
	v_cndmask_b32_e32 v136, v136, v139, vcc
	v_cndmask_b32_e32 v137, v137, v138, vcc
	v_cndmask_b32_e32 v140, v140, v143, vcc
	v_cndmask_b32_e32 v141, v141, v142, vcc
	v_cndmask_b32_e32 v144, v144, v147, vcc
	v_cndmask_b32_e32 v145, v145, v146, vcc
	global_store_dwordx2 v[2:3], v[132:133], off
	global_store_dwordx2 v[148:149], v[136:137], off
	global_store_dwordx2 v[150:151], v[140:141], off
	global_store_dwordx2 v[152:153], v[144:145], off
	v_cvt_pk_bf16_f32 v132, v120, v121
	v_cvt_pk_bf16_f32 v134, v122, v123
	v_cvt_pk_bf16_f32 v136, v116, v117
	v_cvt_pk_bf16_f32 v138, v118, v119
	v_cvt_pk_bf16_f32 v140, v112, v113
	v_cvt_pk_bf16_f32 v142, v114, v115
	v_cvt_pk_bf16_f32 v144, v108, v109
	v_cvt_pk_bf16_f32 v146, v110, v111
	v_mov_b32_dpp v133, v132 quad_perm:[1,0,3,2] row_mask:0xf bank_mask:0xf
	v_mov_b32_dpp v135, v134 quad_perm:[1,0,3,2] row_mask:0xf bank_mask:0xf
	v_mov_b32_dpp v137, v136 quad_perm:[1,0,3,2] row_mask:0xf bank_mask:0xf
	v_mov_b32_dpp v139, v138 quad_perm:[1,0,3,2] row_mask:0xf bank_mask:0xf
	v_mov_b32_dpp v141, v140 quad_perm:[1,0,3,2] row_mask:0xf bank_mask:0xf
	v_mov_b32_dpp v143, v142 quad_perm:[1,0,3,2] row_mask:0xf bank_mask:0xf
	v_mov_b32_dpp v145, v144 quad_perm:[1,0,3,2] row_mask:0xf bank_mask:0xf
	v_mov_b32_dpp v147, v146 quad_perm:[1,0,3,2] row_mask:0xf bank_mask:0xf
	v_perm_b32 v132, v133, v132, v154
	v_perm_b32 v134, v135, v134, v154
	v_perm_b32 v136, v137, v136, v154
	v_perm_b32 v138, v139, v138, v154
	v_perm_b32 v140, v141, v140, v154
	v_perm_b32 v142, v143, v142, v154
	v_perm_b32 v144, v145, v144, v154
	v_perm_b32 v146, v147, v146, v154
	v_mov_b32_dpp v133, v132 quad_perm:[2,3,0,1] row_mask:0xf bank_mask:0xf
	v_mov_b32_dpp v135, v134 quad_perm:[2,3,0,1] row_mask:0xf bank_mask:0xf
	v_mov_b32_dpp v137, v136 quad_perm:[2,3,0,1] row_mask:0xf bank_mask:0xf
	v_mov_b32_dpp v139, v138 quad_perm:[2,3,0,1] row_mask:0xf bank_mask:0xf
	v_mov_b32_dpp v141, v140 quad_perm:[2,3,0,1] row_mask:0xf bank_mask:0xf
	v_mov_b32_dpp v143, v142 quad_perm:[2,3,0,1] row_mask:0xf bank_mask:0xf
	v_mov_b32_dpp v145, v144 quad_perm:[2,3,0,1] row_mask:0xf bank_mask:0xf
	v_mov_b32_dpp v147, v146 quad_perm:[2,3,0,1] row_mask:0xf bank_mask:0xf
	v_cndmask_b32_e32 v132, v132, v135, vcc
	v_cndmask_b32_e32 v133, v133, v134, vcc
	v_cndmask_b32_e32 v136, v136, v139, vcc
	v_cndmask_b32_e32 v137, v137, v138, vcc
	v_cndmask_b32_e32 v140, v140, v143, vcc
	v_cndmask_b32_e32 v141, v141, v142, vcc
	v_cndmask_b32_e32 v144, v144, v147, vcc
	v_cndmask_b32_e32 v145, v145, v146, vcc
	global_store_dwordx2 v[2:3], v[132:133], off offset:32
	global_store_dwordx2 v[148:149], v[136:137], off offset:32
	global_store_dwordx2 v[150:151], v[140:141], off offset:32
	global_store_dwordx2 v[152:153], v[144:145], off offset:32
	v_cvt_pk_bf16_f32 v132, v100, v101
	v_cvt_pk_bf16_f32 v134, v102, v103
	v_cvt_pk_bf16_f32 v136, v96, v97
	v_cvt_pk_bf16_f32 v138, v98, v99
	v_cvt_pk_bf16_f32 v140, v92, v93
	v_cvt_pk_bf16_f32 v142, v94, v95
	v_cvt_pk_bf16_f32 v144, v88, v89
	v_cvt_pk_bf16_f32 v146, v90, v91
	v_mov_b32_dpp v133, v132 quad_perm:[1,0,3,2] row_mask:0xf bank_mask:0xf
	v_mov_b32_dpp v135, v134 quad_perm:[1,0,3,2] row_mask:0xf bank_mask:0xf
	v_mov_b32_dpp v137, v136 quad_perm:[1,0,3,2] row_mask:0xf bank_mask:0xf
	v_mov_b32_dpp v139, v138 quad_perm:[1,0,3,2] row_mask:0xf bank_mask:0xf
	v_mov_b32_dpp v141, v140 quad_perm:[1,0,3,2] row_mask:0xf bank_mask:0xf
	v_mov_b32_dpp v143, v142 quad_perm:[1,0,3,2] row_mask:0xf bank_mask:0xf
	v_mov_b32_dpp v145, v144 quad_perm:[1,0,3,2] row_mask:0xf bank_mask:0xf
	v_mov_b32_dpp v147, v146 quad_perm:[1,0,3,2] row_mask:0xf bank_mask:0xf
	v_perm_b32 v132, v133, v132, v154
	v_perm_b32 v134, v135, v134, v154
	v_perm_b32 v136, v137, v136, v154
	v_perm_b32 v138, v139, v138, v154
	v_perm_b32 v140, v141, v140, v154
	v_perm_b32 v142, v143, v142, v154
	v_perm_b32 v144, v145, v144, v154
	v_perm_b32 v146, v147, v146, v154
	v_mov_b32_dpp v133, v132 quad_perm:[2,3,0,1] row_mask:0xf bank_mask:0xf
	v_mov_b32_dpp v135, v134 quad_perm:[2,3,0,1] row_mask:0xf bank_mask:0xf
	v_mov_b32_dpp v137, v136 quad_perm:[2,3,0,1] row_mask:0xf bank_mask:0xf
	v_mov_b32_dpp v139, v138 quad_perm:[2,3,0,1] row_mask:0xf bank_mask:0xf
	v_mov_b32_dpp v141, v140 quad_perm:[2,3,0,1] row_mask:0xf bank_mask:0xf
	v_mov_b32_dpp v143, v142 quad_perm:[2,3,0,1] row_mask:0xf bank_mask:0xf
	v_mov_b32_dpp v145, v144 quad_perm:[2,3,0,1] row_mask:0xf bank_mask:0xf
	v_mov_b32_dpp v147, v146 quad_perm:[2,3,0,1] row_mask:0xf bank_mask:0xf
	v_cndmask_b32_e32 v132, v132, v135, vcc
	v_cndmask_b32_e32 v133, v133, v134, vcc
	v_cndmask_b32_e32 v136, v136, v139, vcc
	v_cndmask_b32_e32 v137, v137, v138, vcc
	v_cndmask_b32_e32 v140, v140, v143, vcc
	v_cndmask_b32_e32 v141, v141, v142, vcc
	v_cndmask_b32_e32 v144, v144, v147, vcc
	v_cndmask_b32_e32 v145, v145, v146, vcc
	global_store_dwordx2 v[2:3], v[132:133], off offset:64
	global_store_dwordx2 v[148:149], v[136:137], off offset:64
	global_store_dwordx2 v[150:151], v[140:141], off offset:64
	global_store_dwordx2 v[152:153], v[144:145], off offset:64
	v_cvt_pk_bf16_f32 v132, v80, v81
	v_cvt_pk_bf16_f32 v134, v82, v83
	v_cvt_pk_bf16_f32 v136, v76, v77
	v_cvt_pk_bf16_f32 v138, v78, v79
	v_cvt_pk_bf16_f32 v140, v72, v73
	v_cvt_pk_bf16_f32 v142, v74, v75
	v_cvt_pk_bf16_f32 v144, v68, v69
	v_cvt_pk_bf16_f32 v146, v70, v71
	v_mov_b32_dpp v133, v132 quad_perm:[1,0,3,2] row_mask:0xf bank_mask:0xf
	v_mov_b32_dpp v135, v134 quad_perm:[1,0,3,2] row_mask:0xf bank_mask:0xf
	v_mov_b32_dpp v137, v136 quad_perm:[1,0,3,2] row_mask:0xf bank_mask:0xf
	v_mov_b32_dpp v139, v138 quad_perm:[1,0,3,2] row_mask:0xf bank_mask:0xf
	v_mov_b32_dpp v141, v140 quad_perm:[1,0,3,2] row_mask:0xf bank_mask:0xf
	v_mov_b32_dpp v143, v142 quad_perm:[1,0,3,2] row_mask:0xf bank_mask:0xf
	v_mov_b32_dpp v145, v144 quad_perm:[1,0,3,2] row_mask:0xf bank_mask:0xf
	v_mov_b32_dpp v147, v146 quad_perm:[1,0,3,2] row_mask:0xf bank_mask:0xf
	v_perm_b32 v132, v133, v132, v154
	v_perm_b32 v134, v135, v134, v154
	v_perm_b32 v136, v137, v136, v154
	v_perm_b32 v138, v139, v138, v154
	v_perm_b32 v140, v141, v140, v154
	v_perm_b32 v142, v143, v142, v154
	v_perm_b32 v144, v145, v144, v154
	v_perm_b32 v146, v147, v146, v154
	v_mov_b32_dpp v133, v132 quad_perm:[2,3,0,1] row_mask:0xf bank_mask:0xf
	v_mov_b32_dpp v135, v134 quad_perm:[2,3,0,1] row_mask:0xf bank_mask:0xf
	v_mov_b32_dpp v137, v136 quad_perm:[2,3,0,1] row_mask:0xf bank_mask:0xf
	v_mov_b32_dpp v139, v138 quad_perm:[2,3,0,1] row_mask:0xf bank_mask:0xf
	v_mov_b32_dpp v141, v140 quad_perm:[2,3,0,1] row_mask:0xf bank_mask:0xf
	v_mov_b32_dpp v143, v142 quad_perm:[2,3,0,1] row_mask:0xf bank_mask:0xf
	v_mov_b32_dpp v145, v144 quad_perm:[2,3,0,1] row_mask:0xf bank_mask:0xf
	v_mov_b32_dpp v147, v146 quad_perm:[2,3,0,1] row_mask:0xf bank_mask:0xf
	v_cndmask_b32_e32 v132, v132, v135, vcc
	v_cndmask_b32_e32 v133, v133, v134, vcc
	v_cndmask_b32_e32 v136, v136, v139, vcc
	v_cndmask_b32_e32 v137, v137, v138, vcc
	v_cndmask_b32_e32 v140, v140, v143, vcc
	v_cndmask_b32_e32 v141, v141, v142, vcc
	v_cndmask_b32_e32 v144, v144, v147, vcc
	v_cndmask_b32_e32 v145, v145, v146, vcc
	global_store_dwordx2 v[2:3], v[132:133], off offset:96
	global_store_dwordx2 v[148:149], v[136:137], off offset:96
	global_store_dwordx2 v[150:151], v[140:141], off offset:96
	global_store_dwordx2 v[152:153], v[144:145], off offset:96
	v_cvt_pk_bf16_f32 v132, v64, v65
	v_cvt_pk_bf16_f32 v134, v66, v67
	v_cvt_pk_bf16_f32 v136, v60, v61
	v_cvt_pk_bf16_f32 v138, v62, v63
	v_cvt_pk_bf16_f32 v140, v56, v57
	v_cvt_pk_bf16_f32 v142, v58, v59
	v_cvt_pk_bf16_f32 v144, v52, v53
	v_cvt_pk_bf16_f32 v146, v54, v55
	v_mov_b32_dpp v133, v132 quad_perm:[1,0,3,2] row_mask:0xf bank_mask:0xf
	v_mov_b32_dpp v135, v134 quad_perm:[1,0,3,2] row_mask:0xf bank_mask:0xf
	v_mov_b32_dpp v137, v136 quad_perm:[1,0,3,2] row_mask:0xf bank_mask:0xf
	v_mov_b32_dpp v139, v138 quad_perm:[1,0,3,2] row_mask:0xf bank_mask:0xf
	v_mov_b32_dpp v141, v140 quad_perm:[1,0,3,2] row_mask:0xf bank_mask:0xf
	v_mov_b32_dpp v143, v142 quad_perm:[1,0,3,2] row_mask:0xf bank_mask:0xf
	v_mov_b32_dpp v145, v144 quad_perm:[1,0,3,2] row_mask:0xf bank_mask:0xf
	v_mov_b32_dpp v147, v146 quad_perm:[1,0,3,2] row_mask:0xf bank_mask:0xf
	v_perm_b32 v132, v133, v132, v154
	v_perm_b32 v134, v135, v134, v154
	v_perm_b32 v136, v137, v136, v154
	v_perm_b32 v138, v139, v138, v154
	v_perm_b32 v140, v141, v140, v154
	v_perm_b32 v142, v143, v142, v154
	v_perm_b32 v144, v145, v144, v154
	v_perm_b32 v146, v147, v146, v154
	v_mov_b32_dpp v133, v132 quad_perm:[2,3,0,1] row_mask:0xf bank_mask:0xf
	v_mov_b32_dpp v135, v134 quad_perm:[2,3,0,1] row_mask:0xf bank_mask:0xf
	v_mov_b32_dpp v137, v136 quad_perm:[2,3,0,1] row_mask:0xf bank_mask:0xf
	v_mov_b32_dpp v139, v138 quad_perm:[2,3,0,1] row_mask:0xf bank_mask:0xf
	v_mov_b32_dpp v141, v140 quad_perm:[2,3,0,1] row_mask:0xf bank_mask:0xf
	v_mov_b32_dpp v143, v142 quad_perm:[2,3,0,1] row_mask:0xf bank_mask:0xf
	v_mov_b32_dpp v145, v144 quad_perm:[2,3,0,1] row_mask:0xf bank_mask:0xf
	v_mov_b32_dpp v147, v146 quad_perm:[2,3,0,1] row_mask:0xf bank_mask:0xf
	v_cndmask_b32_e32 v132, v132, v135, vcc
	v_cndmask_b32_e32 v133, v133, v134, vcc
	v_cndmask_b32_e32 v136, v136, v139, vcc
	v_cndmask_b32_e32 v137, v137, v138, vcc
	v_cndmask_b32_e32 v140, v140, v143, vcc
	v_cndmask_b32_e32 v141, v141, v142, vcc
	v_cndmask_b32_e32 v144, v144, v147, vcc
	v_cndmask_b32_e32 v145, v145, v146, vcc
	global_store_dwordx2 v[2:3], v[132:133], off offset:256
	global_store_dwordx2 v[148:149], v[136:137], off offset:256
	global_store_dwordx2 v[150:151], v[140:141], off offset:256
	global_store_dwordx2 v[152:153], v[144:145], off offset:256
	v_cvt_pk_bf16_f32 v132, v48, v49
	v_cvt_pk_bf16_f32 v134, v50, v51
	v_cvt_pk_bf16_f32 v136, v44, v45
	v_cvt_pk_bf16_f32 v138, v46, v47
	v_cvt_pk_bf16_f32 v140, v40, v41
	v_cvt_pk_bf16_f32 v142, v42, v43
	v_cvt_pk_bf16_f32 v144, v36, v37
	v_cvt_pk_bf16_f32 v146, v38, v39
	v_mov_b32_dpp v133, v132 quad_perm:[1,0,3,2] row_mask:0xf bank_mask:0xf
	v_mov_b32_dpp v135, v134 quad_perm:[1,0,3,2] row_mask:0xf bank_mask:0xf
	v_mov_b32_dpp v137, v136 quad_perm:[1,0,3,2] row_mask:0xf bank_mask:0xf
	v_mov_b32_dpp v139, v138 quad_perm:[1,0,3,2] row_mask:0xf bank_mask:0xf
	v_mov_b32_dpp v141, v140 quad_perm:[1,0,3,2] row_mask:0xf bank_mask:0xf
	v_mov_b32_dpp v143, v142 quad_perm:[1,0,3,2] row_mask:0xf bank_mask:0xf
	v_mov_b32_dpp v145, v144 quad_perm:[1,0,3,2] row_mask:0xf bank_mask:0xf
	v_mov_b32_dpp v147, v146 quad_perm:[1,0,3,2] row_mask:0xf bank_mask:0xf
	v_perm_b32 v132, v133, v132, v154
	v_perm_b32 v134, v135, v134, v154
	v_perm_b32 v136, v137, v136, v154
	v_perm_b32 v138, v139, v138, v154
	v_perm_b32 v140, v141, v140, v154
	v_perm_b32 v142, v143, v142, v154
	v_perm_b32 v144, v145, v144, v154
	v_perm_b32 v146, v147, v146, v154
	v_mov_b32_dpp v133, v132 quad_perm:[2,3,0,1] row_mask:0xf bank_mask:0xf
	v_mov_b32_dpp v135, v134 quad_perm:[2,3,0,1] row_mask:0xf bank_mask:0xf
	v_mov_b32_dpp v137, v136 quad_perm:[2,3,0,1] row_mask:0xf bank_mask:0xf
	v_mov_b32_dpp v139, v138 quad_perm:[2,3,0,1] row_mask:0xf bank_mask:0xf
	v_mov_b32_dpp v141, v140 quad_perm:[2,3,0,1] row_mask:0xf bank_mask:0xf
	v_mov_b32_dpp v143, v142 quad_perm:[2,3,0,1] row_mask:0xf bank_mask:0xf
	v_mov_b32_dpp v145, v144 quad_perm:[2,3,0,1] row_mask:0xf bank_mask:0xf
	v_mov_b32_dpp v147, v146 quad_perm:[2,3,0,1] row_mask:0xf bank_mask:0xf
	v_cndmask_b32_e32 v132, v132, v135, vcc
	v_cndmask_b32_e32 v133, v133, v134, vcc
	v_cndmask_b32_e32 v136, v136, v139, vcc
	v_cndmask_b32_e32 v137, v137, v138, vcc
	v_cndmask_b32_e32 v140, v140, v143, vcc
	v_cndmask_b32_e32 v141, v141, v142, vcc
	v_cndmask_b32_e32 v144, v144, v147, vcc
	v_cndmask_b32_e32 v145, v145, v146, vcc
	global_store_dwordx2 v[2:3], v[132:133], off offset:288
	global_store_dwordx2 v[148:149], v[136:137], off offset:288
	global_store_dwordx2 v[150:151], v[140:141], off offset:288
	global_store_dwordx2 v[152:153], v[144:145], off offset:288
	v_cvt_pk_bf16_f32 v132, v32, v33
	v_cvt_pk_bf16_f32 v134, v34, v35
	v_cvt_pk_bf16_f32 v136, v28, v29
	v_cvt_pk_bf16_f32 v138, v30, v31
	v_cvt_pk_bf16_f32 v140, v24, v25
	v_cvt_pk_bf16_f32 v142, v26, v27
	v_cvt_pk_bf16_f32 v144, v20, v21
	v_cvt_pk_bf16_f32 v146, v22, v23
	v_mov_b32_dpp v133, v132 quad_perm:[1,0,3,2] row_mask:0xf bank_mask:0xf
	v_mov_b32_dpp v135, v134 quad_perm:[1,0,3,2] row_mask:0xf bank_mask:0xf
	v_mov_b32_dpp v137, v136 quad_perm:[1,0,3,2] row_mask:0xf bank_mask:0xf
	v_mov_b32_dpp v139, v138 quad_perm:[1,0,3,2] row_mask:0xf bank_mask:0xf
	v_mov_b32_dpp v141, v140 quad_perm:[1,0,3,2] row_mask:0xf bank_mask:0xf
	v_mov_b32_dpp v143, v142 quad_perm:[1,0,3,2] row_mask:0xf bank_mask:0xf
	v_mov_b32_dpp v145, v144 quad_perm:[1,0,3,2] row_mask:0xf bank_mask:0xf
	v_mov_b32_dpp v147, v146 quad_perm:[1,0,3,2] row_mask:0xf bank_mask:0xf
	v_perm_b32 v132, v133, v132, v154
	v_perm_b32 v134, v135, v134, v154
	v_perm_b32 v136, v137, v136, v154
	v_perm_b32 v138, v139, v138, v154
	v_perm_b32 v140, v141, v140, v154
	v_perm_b32 v142, v143, v142, v154
	v_perm_b32 v144, v145, v144, v154
	v_perm_b32 v146, v147, v146, v154
	v_mov_b32_dpp v133, v132 quad_perm:[2,3,0,1] row_mask:0xf bank_mask:0xf
	v_mov_b32_dpp v135, v134 quad_perm:[2,3,0,1] row_mask:0xf bank_mask:0xf
	v_mov_b32_dpp v137, v136 quad_perm:[2,3,0,1] row_mask:0xf bank_mask:0xf
	v_mov_b32_dpp v139, v138 quad_perm:[2,3,0,1] row_mask:0xf bank_mask:0xf
	v_mov_b32_dpp v141, v140 quad_perm:[2,3,0,1] row_mask:0xf bank_mask:0xf
	v_mov_b32_dpp v143, v142 quad_perm:[2,3,0,1] row_mask:0xf bank_mask:0xf
	v_mov_b32_dpp v145, v144 quad_perm:[2,3,0,1] row_mask:0xf bank_mask:0xf
	v_mov_b32_dpp v147, v146 quad_perm:[2,3,0,1] row_mask:0xf bank_mask:0xf
	v_cndmask_b32_e32 v132, v132, v135, vcc
	v_cndmask_b32_e32 v133, v133, v134, vcc
	v_cndmask_b32_e32 v136, v136, v139, vcc
	v_cndmask_b32_e32 v137, v137, v138, vcc
	v_cndmask_b32_e32 v140, v140, v143, vcc
	v_cndmask_b32_e32 v141, v141, v142, vcc
	v_cndmask_b32_e32 v144, v144, v147, vcc
	v_cndmask_b32_e32 v145, v145, v146, vcc
	global_store_dwordx2 v[2:3], v[132:133], off offset:320
	global_store_dwordx2 v[148:149], v[136:137], off offset:320
	global_store_dwordx2 v[150:151], v[140:141], off offset:320
	global_store_dwordx2 v[152:153], v[144:145], off offset:320
	v_cvt_pk_bf16_f32 v132, v16, v17
	v_cvt_pk_bf16_f32 v134, v18, v19
	v_cvt_pk_bf16_f32 v136, v12, v13
	v_cvt_pk_bf16_f32 v138, v14, v15
	v_cvt_pk_bf16_f32 v140, v8, v9
	v_cvt_pk_bf16_f32 v142, v10, v11
	v_cvt_pk_bf16_f32 v144, v4, v5
	v_cvt_pk_bf16_f32 v146, v6, v7
	v_mov_b32_dpp v133, v132 quad_perm:[1,0,3,2] row_mask:0xf bank_mask:0xf
	v_mov_b32_dpp v135, v134 quad_perm:[1,0,3,2] row_mask:0xf bank_mask:0xf
	v_mov_b32_dpp v137, v136 quad_perm:[1,0,3,2] row_mask:0xf bank_mask:0xf
	v_mov_b32_dpp v139, v138 quad_perm:[1,0,3,2] row_mask:0xf bank_mask:0xf
	v_mov_b32_dpp v141, v140 quad_perm:[1,0,3,2] row_mask:0xf bank_mask:0xf
	v_mov_b32_dpp v143, v142 quad_perm:[1,0,3,2] row_mask:0xf bank_mask:0xf
	v_mov_b32_dpp v145, v144 quad_perm:[1,0,3,2] row_mask:0xf bank_mask:0xf
	v_mov_b32_dpp v147, v146 quad_perm:[1,0,3,2] row_mask:0xf bank_mask:0xf
	v_perm_b32 v132, v133, v132, v154
	v_perm_b32 v134, v135, v134, v154
	v_perm_b32 v136, v137, v136, v154
	v_perm_b32 v138, v139, v138, v154
	v_perm_b32 v140, v141, v140, v154
	v_perm_b32 v142, v143, v142, v154
	v_perm_b32 v144, v145, v144, v154
	v_perm_b32 v146, v147, v146, v154
	v_mov_b32_dpp v133, v132 quad_perm:[2,3,0,1] row_mask:0xf bank_mask:0xf
	v_mov_b32_dpp v135, v134 quad_perm:[2,3,0,1] row_mask:0xf bank_mask:0xf
	v_mov_b32_dpp v137, v136 quad_perm:[2,3,0,1] row_mask:0xf bank_mask:0xf
	v_mov_b32_dpp v139, v138 quad_perm:[2,3,0,1] row_mask:0xf bank_mask:0xf
	v_mov_b32_dpp v141, v140 quad_perm:[2,3,0,1] row_mask:0xf bank_mask:0xf
	v_mov_b32_dpp v143, v142 quad_perm:[2,3,0,1] row_mask:0xf bank_mask:0xf
	v_mov_b32_dpp v145, v144 quad_perm:[2,3,0,1] row_mask:0xf bank_mask:0xf
	v_mov_b32_dpp v147, v146 quad_perm:[2,3,0,1] row_mask:0xf bank_mask:0xf
	v_cndmask_b32_e32 v132, v132, v135, vcc
	v_cndmask_b32_e32 v133, v133, v134, vcc
	v_cndmask_b32_e32 v136, v136, v139, vcc
	v_cndmask_b32_e32 v137, v137, v138, vcc
	v_cndmask_b32_e32 v140, v140, v143, vcc
	v_cndmask_b32_e32 v141, v141, v142, vcc
	v_cndmask_b32_e32 v144, v144, v147, vcc
	v_cndmask_b32_e32 v145, v145, v146, vcc
	global_store_dwordx2 v[2:3], v[132:133], off offset:352
	global_store_dwordx2 v[148:149], v[136:137], off offset:352
	global_store_dwordx2 v[150:151], v[140:141], off offset:352
	global_store_dwordx2 v[152:153], v[144:145], off offset:352
	s_mov_b64 s[2:3], 0
